# conv: gtm halo load no longer drains all gate loads before the meta pass (halo into dedicated reg, shift deferred to consumer)
# speedup vs baseline: 1.0051x; 1.0051x over previous
; template <int NQ, int NB, int L>
; __device__ __forceinline__ void conv_unit(LAS unsigned char* lds, const Args& a, int j, int seq0, int c, int tid) {
;     ...
;         const bf16_t* X = (o == 0 ? X1 : X2) + xrow_off;
;         const float w0 = cw[o * 1024 + c], w1 = cw[3072 + o * 1024 + c], w2 = cw[2 * 3072 + o * 1024 + c], bb = cb[o * 1024 + c];
;         GateRaw gt[4][4];
;         {
;             const int mb = mw + QS * q + 4 * g; const bf16_t* Xb = X + mb;
; #pragma unroll
;             for (int gi = 0; gi < 4; ++gi)
; #pragma unroll
;                 for (int t = 0; t < 4; ++t) { constexpr int dummy = 0; (void)dummy; const int off = GS * gi + 16 * t;
;                     GateRaw r; r.raw = *(const u32x2*)(Xb + off);
;                     const unsigned xm = (unsigned)Xb[off - 1]; unsigned xp = (unsigned)Xb[off + 4];
;                     if (mb + off + 4 >= L) xp = 0u;
;                     r.halo = xm | (xp << 16); gt[gi][t] = r; }
;         }
;         const GateRaw gtm = gate_load(X, 4 * g, L);
.LBB0_1352:
	s_and_b64 s[44:45], exec, s[44:45]
	s_cselect_b32 s56, s81, 0x25700000
	v_mfma_f32_16x16x32_bf16 v[90:93], v[70:73], v[82:85], v[90:93]
	v_mov_b32_e32 v32, 0x6000
	v_mov_b32_e32 v165, v33
	v_mov_b32_e32 v127, 0
	v_mov_b32_e32 v204, 0
	v_mfma_f32_16x16x32_bf16 v[70:73], v[74:77], v[82:85], v[86:89]
	v_lshl_add_u64 v[74:75], v[138:139], 0, s[56:57]
	s_or_b32 s56, s70, s62
	s_lshl_b64 s[44:45], s[56:57], 2
	s_add_u32 s94, s87, s44
	s_addc_u32 s95, s88, s45
	s_add_i32 s56, s85, s70
	s_lshl_b64 s[70:71], s[56:57], 2
	s_add_u32 s70, s87, s70
	s_addc_u32 s71, s88, s71
	s_add_u32 s44, s89, s44
	s_addc_u32 s45, s90, s45
	v_lshl_add_u64 v[76:77], v[140:141], 1, v[74:75]
	v_mfma_f32_16x16x32_bf16 v[78:81], v[78:81], v[82:85], v[94:97]
	global_load_dword v83, v33, s[94:95]
	global_load_dword v85, v33, s[70:71]
	global_load_dword v89, v33, s[44:45]
	global_load_dword v87, v32, s[94:95]
	global_load_dwordx2 v[124:125], v[76:77], off offset:32
	global_load_ushort v187, v[76:77], off offset:30
	global_load_ushort v188, v[76:77], off offset:40
	global_load_dwordx2 v[122:123], v[76:77], off offset:64
	global_load_ushort v185, v[76:77], off offset:62
	global_load_ushort v186, v[76:77], off offset:72
	global_load_dwordx2 v[120:121], v[76:77], off offset:96
	global_load_ushort v183, v[76:77], off offset:94
	global_load_ushort v184, v[76:77], off offset:104
	global_load_dwordx2 v[118:119], v[76:77], off offset:128
	global_load_ushort v181, v[76:77], off offset:126
	global_load_ushort v182, v[76:77], off offset:136
	s_waitcnt lgkmcnt(0)
	global_load_dwordx2 v[116:117], v[76:77], off offset:288
	global_load_ushort v179, v[76:77], off offset:286
	global_load_ushort v180, v[76:77], off offset:296
	global_load_dwordx2 v[114:115], v[76:77], off offset:320
	global_load_ushort v177, v[76:77], off offset:318
	global_load_ushort v178, v[76:77], off offset:328
	global_load_dwordx2 v[112:113], v[76:77], off offset:352
	global_load_ushort v175, v[76:77], off offset:350
	global_load_ushort v176, v[76:77], off offset:360
	global_load_dwordx2 v[110:111], v[76:77], off offset:384
	global_load_ushort v173, v[76:77], off offset:382
	global_load_ushort v174, v[76:77], off offset:392
	global_load_dwordx2 v[108:109], v[76:77], off offset:544
	global_load_ushort v171, v[76:77], off offset:542
	global_load_ushort v172, v[76:77], off offset:552
	global_load_dwordx2 v[106:107], v[76:77], off offset:576
	global_load_ushort v169, v[76:77], off offset:574
	global_load_ushort v170, v[76:77], off offset:584
	global_load_dwordx2 v[104:105], v[76:77], off offset:608
	global_load_ushort v167, v[76:77], off offset:606
	global_load_ushort v168, v[76:77], off offset:616
	global_load_dwordx2 v[102:103], v[76:77], off offset:640
	global_load_ushort v137, v[76:77], off offset:638
	global_load_ushort v166, v[76:77], off offset:648
	global_load_dwordx2 v[100:101], v[76:77], off offset:800
	global_load_ushort v135, v[76:77], off offset:798
	global_load_ushort v136, v[76:77], off offset:808
	global_load_dwordx2 v[98:99], v[76:77], off offset:832
	global_load_ushort v133, v[76:77], off offset:830
	global_load_ushort v134, v[76:77], off offset:840
	global_load_dwordx2 v[96:97], v[76:77], off offset:864
	global_load_ushort v131, v[76:77], off offset:862
	global_load_ushort v132, v[76:77], off offset:872
	global_load_dwordx2 v[94:95], v[76:77], off offset:896
	global_load_ushort v32, v[76:77], off offset:894
	global_load_ushort v130, v[76:77], off offset:904
	v_lshl_add_u64 v[74:75], v[74:75], 0, v[164:165]
	global_load_dwordx2 v[128:129], v[74:75], off
	v_mov_b32_e32 v77, 0
	s_and_saveexec_b64 s[44:45], s[2:3]
	s_cbranch_execz .LBB0_1354
	global_load_ushort v204, v[74:75], off offset:-2

; #define LAS __attribute__((address_space(3)))
; __device__ __forceinline__ unsigned cvtpk(float lo, float hi) { f32x2 v = {lo, hi}; bf16x2_t b = __builtin_convertvector(v, bf16x2_t); return __builtin_bit_cast(unsigned, b); }
; template <int NQ, int NB, int L>
; __device__ __forceinline__ void conv_unit(LAS unsigned char* lds, const Args& a, int j, int seq0, int c, int tid) {
;     ...
;         *(LAS f32x4*)(lds + RED_OFF + (w * 64 + lane) * 16) = macc;
;         __syncthreads();
;         if (w == 0 && q == 0) {
;             f32x4 s = (f32x4){0.f, 0.f, 0.f, 0.f};
; #pragma unroll
;             for (int ww = 0; ww < 8; ++ww) s += *(const LAS f32x4*)(lds + RED_OFF + (ww * 64 + lane) * 16);
;             const int m = 4 * g;
;             const f32x4 z = gate_eval(gtm, w0, w1, w2, bb) * s;
;             u32x2 pk; pk.x = cvtpk(z[0], z[1]); pk.y = cvtpk(z[2], z[3]);
;             if (o == 0) *(LAS u32x2*)(lds + U_OFF + (b * LPD + PADL + m) * 2) = pk;
;             else *(u32x2*)(V + xrow_off + m) = pk;
.LBB0_1359:
	s_andn2_saveexec_b64 s[44:45], s[44:45]
	s_cbranch_execz .LBB0_1364
	ds_read_b128 v[74:77], v223
	s_waitcnt vmcnt(1)
	v_lshlrev_b32_e32 v86, 16, v128
	v_and_b32_e32 v128, 0xffff0000, v128
	s_waitcnt vmcnt(0)
	v_lshlrev_b32_e32 v127, 16, v204
	v_lshlrev_b32_e32 v147, 16, v126
	v_and_b32_e32 v146, 0xffff0000, v129
	s_waitcnt lgkmcnt(0)
	v_pk_add_f32 v[148:149], v[76:77], 0 op_sel_hi:[1,0]
	v_pk_add_f32 v[150:151], v[74:75], 0 op_sel_hi:[1,0]
	ds_read_b128 v[74:77], v223 offset:1024
	v_lshlrev_b32_e32 v129, 16, v129
	v_mov_b32_e32 v82, v85
	v_mov_b32_e32 v126, v128
	v_mov_b32_e32 v84, v85
	s_waitcnt lgkmcnt(0)
	v_pk_add_f32 v[148:149], v[148:149], v[76:77]
	v_pk_add_f32 v[150:151], v[150:151], v[74:75]
	ds_read_b128 v[74:77], v223 offset:2048
	v_pk_mul_f32 v[126:127], v[82:83], v[126:127]
	v_mov_b32_e32 v88, v89
	v_pk_fma_f32 v[126:127], v[82:83], v[86:87], v[126:127] op_sel:[0,0,1] op_sel_hi:[1,0,0]
	v_mov_b32_e32 v86, v87
	s_waitcnt lgkmcnt(0)
	v_pk_add_f32 v[148:149], v[148:149], v[76:77]
	v_pk_add_f32 v[150:151], v[150:151], v[74:75]
	ds_read_b128 v[74:77], v223 offset:3072
	v_mov_b32_e32 v82, v83
	v_pk_fma_f32 v[126:127], v[86:87], v[128:129], v[126:127] op_sel_hi:[0,1,1]
	v_pk_add_f32 v[126:127], v[88:89], v[126:127] op_sel_hi:[0,1]
	s_mov_b64 s[70:71], -1
	s_waitcnt lgkmcnt(0)
	v_pk_add_f32 v[148:149], v[148:149], v[76:77]
	v_pk_add_f32 v[150:151], v[150:151], v[74:75]
	ds_read_b128 v[74:77], v223 offset:4096
	s_and_b64 vcc, exec, s[66:67]
	s_waitcnt lgkmcnt(0)
	v_pk_add_f32 v[148:149], v[148:149], v[76:77]
	v_pk_add_f32 v[150:151], v[150:151], v[74:75]
	ds_read_b128 v[74:77], v223 offset:5120
	s_waitcnt lgkmcnt(0)
	v_pk_add_f32 v[148:149], v[148:149], v[76:77]
	v_pk_add_f32 v[150:151], v[150:151], v[74:75]
	ds_read_b128 v[74:77], v223 offset:6144
	s_waitcnt lgkmcnt(0)
	v_pk_add_f32 v[148:149], v[148:149], v[76:77]
	v_pk_add_f32 v[150:151], v[150:151], v[74:75]
	ds_read_b128 v[74:77], v223 offset:7168
	s_waitcnt lgkmcnt(0)
	v_pk_add_f32 v[76:77], v[148:149], v[76:77]
	v_pk_mov_b32 v[148:149], v[128:129], v[146:147] op_sel:[1,0]
	v_pk_add_f32 v[74:75], v[150:151], v[74:75]
	v_pk_mul_f32 v[148:149], v[84:85], v[148:149] op_sel_hi:[0,1]
	v_pk_fma_f32 v[128:129], v[82:83], v[128:129], v[148:149] op_sel_hi:[0,1,1]
	v_pk_fma_f32 v[128:129], v[86:87], v[146:147], v[128:129] op_sel_hi:[0,1,1]
	v_pk_add_f32 v[128:129], v[88:89], v[128:129] op_sel_hi:[0,1]
	v_pk_mul_f32 v[76:77], v[128:129], v[76:77]
	v_pk_mul_f32 v[74:75], v[126:127], v[74:75]
	s_nop 0
	v_cvt_pk_bf16_f32 v74, v74, v75
	v_cvt_pk_bf16_f32 v75, v76, v77
	s_cbranch_vccz .LBB0_1362
	global_store_dwordx2 v[142:143], v[74:75], off
	s_mov_b64 s[70:71], 0

; template <int NQ, int NB, int L>
; __device__ __forceinline__ void conv_unit(LAS unsigned char* lds, const Args& a, int j, int seq0, int c, int tid) {
;     ...
;         const bf16_t* X = (o == 0 ? X1 : X2) + xrow_off;
;         const float w0 = cw[o * 1024 + c], w1 = cw[3072 + o * 1024 + c], w2 = cw[2 * 3072 + o * 1024 + c], bb = cb[o * 1024 + c];
;         GateRaw gt[4][4];
;         {
;             const int mb = mw + QS * q + 4 * g; const bf16_t* Xb = X + mb;
; #pragma unroll
;             for (int gi = 0; gi < 4; ++gi)
; #pragma unroll
;                 for (int t = 0; t < 4; ++t) { constexpr int dummy = 0; (void)dummy; const int off = GS * gi + 16 * t;
;                     GateRaw r; r.raw = *(const u32x2*)(Xb + off);
;                     const unsigned xm = (unsigned)Xb[off - 1]; unsigned xp = (unsigned)Xb[off + 4];
;                     if (mb + off + 4 >= L) xp = 0u;
;                     r.halo = xm | (xp << 16); gt[gi][t] = r; }
;         }
;         const GateRaw gtm = gate_load(X, 4 * g, L);
.LBB0_1557:
	s_and_b64 s[74:75], exec, s[74:75]
	s_cselect_b32 s56, s81, 0x25700000
	s_add_i32 s74, s48, s52
	s_ashr_i32 s49, s48, 31
	s_ashr_i32 s75, s74, 31
	s_lshl_b64 s[48:49], s[48:49], 2
	s_add_u32 s48, s62, s48
	s_addc_u32 s49, s63, s49
	v_mfma_f32_16x16x32_bf16 v[94:97], v[78:81], v[90:93], v[94:97]
	v_mov_b32_e32 v177, v33
	v_mov_b32_e32 v135, 0
	v_mov_b32_e32 v204, 0
	v_mfma_f32_16x16x32_bf16 v[86:89], v[86:89], v[90:93], v[102:105]
	v_mfma_f32_16x16x32_bf16 v[78:81], v[82:85], v[90:93], v[98:101]
	global_load_dword v91, v33, s[48:49]
	s_add_i32 s48, s74, 0xc00
	s_ashr_i32 s49, s48, 31
	s_lshl_b64 s[48:49], s[48:49], 2
	s_add_u32 s48, s87, s48
	s_addc_u32 s49, s88, s49
	global_load_dword v93, v33, s[48:49]
	s_add_i32 s48, s74, 0x1800
	s_ashr_i32 s49, s48, 31
	s_lshl_b64 s[48:49], s[48:49], 2
	s_add_u32 s48, s87, s48
	s_addc_u32 s49, s88, s49
	global_load_dword v99, v33, s[48:49]
	s_lshl_b64 s[48:49], s[74:75], 2
	v_lshl_add_u64 v[82:83], v[158:159], 0, s[56:57]
	s_add_u32 s48, s89, s48
	s_addc_u32 s49, s90, s49
	v_lshl_add_u64 v[84:85], v[160:161], 1, v[82:83]
	global_load_dword v101, v33, s[48:49]
	global_load_dwordx2 v[132:133], v[84:85], off offset:128
	global_load_ushort v199, v[84:85], off offset:126
	global_load_ushort v200, v[84:85], off offset:136
	global_load_dwordx2 v[130:131], v[84:85], off offset:160
	global_load_ushort v197, v[84:85], off offset:158
	global_load_ushort v198, v[84:85], off offset:168
	global_load_dwordx2 v[128:129], v[84:85], off offset:192
	global_load_ushort v195, v[84:85], off offset:190
	global_load_ushort v196, v[84:85], off offset:200
	global_load_dwordx2 v[126:127], v[84:85], off offset:224
	global_load_ushort v193, v[84:85], off offset:222
	global_load_ushort v194, v[84:85], off offset:232
	s_waitcnt lgkmcnt(0)
	global_load_dwordx2 v[124:125], v[84:85], off offset:640
	global_load_ushort v191, v[84:85], off offset:638
	global_load_ushort v192, v[84:85], off offset:648
	global_load_dwordx2 v[122:123], v[84:85], off offset:672
	global_load_ushort v189, v[84:85], off offset:670
	global_load_ushort v190, v[84:85], off offset:680
	global_load_dwordx2 v[120:121], v[84:85], off offset:704
	global_load_ushort v187, v[84:85], off offset:702
	global_load_ushort v188, v[84:85], off offset:712
	global_load_dwordx2 v[118:119], v[84:85], off offset:736
	global_load_ushort v185, v[84:85], off offset:734
	global_load_ushort v186, v[84:85], off offset:744
	global_load_dwordx2 v[116:117], v[84:85], off offset:1152
	global_load_ushort v183, v[84:85], off offset:1150
	global_load_ushort v184, v[84:85], off offset:1160
	global_load_dwordx2 v[114:115], v[84:85], off offset:1184
	global_load_ushort v181, v[84:85], off offset:1182
	global_load_ushort v182, v[84:85], off offset:1192
	global_load_dwordx2 v[112:113], v[84:85], off offset:1216
	global_load_ushort v179, v[84:85], off offset:1214
	global_load_ushort v180, v[84:85], off offset:1224
	global_load_dwordx2 v[110:111], v[84:85], off offset:1248
	global_load_ushort v145, v[84:85], off offset:1246
	global_load_ushort v178, v[84:85], off offset:1256
	global_load_dwordx2 v[108:109], v[84:85], off offset:1664
	global_load_ushort v143, v[84:85], off offset:1662
	global_load_ushort v144, v[84:85], off offset:1672
	global_load_dwordx2 v[106:107], v[84:85], off offset:1696
	global_load_ushort v141, v[84:85], off offset:1694
	global_load_ushort v142, v[84:85], off offset:1704
	global_load_dwordx2 v[104:105], v[84:85], off offset:1728
	global_load_ushort v139, v[84:85], off offset:1726
	global_load_ushort v140, v[84:85], off offset:1736
	global_load_dwordx2 v[102:103], v[84:85], off offset:1760
	global_load_ushort v32, v[84:85], off offset:1758
	global_load_ushort v138, v[84:85], off offset:1768
	v_lshl_add_u64 v[82:83], v[82:83], 0, v[176:177]
	global_load_dwordx2 v[136:137], v[82:83], off offset:96
	v_mov_b32_e32 v85, 0
	s_and_saveexec_b64 s[48:49], s[2:3]
	s_cbranch_execz .LBB0_1559
	global_load_ushort v204, v[82:83], off offset:94

; #define LAS __attribute__((address_space(3)))
; __device__ __forceinline__ unsigned cvtpk(float lo, float hi) { f32x2 v = {lo, hi}; bf16x2_t b = __builtin_convertvector(v, bf16x2_t); return __builtin_bit_cast(unsigned, b); }
; template <int NQ, int NB, int L>
; __device__ __forceinline__ void conv_unit(LAS unsigned char* lds, const Args& a, int j, int seq0, int c, int tid) {
;     ...
;         *(LAS f32x4*)(lds + RED_OFF + (w * 64 + lane) * 16) = macc;
;         __syncthreads();
;         if (w == 0 && q == 0) {
;             f32x4 s = (f32x4){0.f, 0.f, 0.f, 0.f};
; #pragma unroll
;             for (int ww = 0; ww < 8; ++ww) s += *(const LAS f32x4*)(lds + RED_OFF + (ww * 64 + lane) * 16);
;             const int m = 4 * g;
;             const f32x4 z = gate_eval(gtm, w0, w1, w2, bb) * s;
;             u32x2 pk; pk.x = cvtpk(z[0], z[1]); pk.y = cvtpk(z[2], z[3]);
;             if (o == 0) *(LAS u32x2*)(lds + U_OFF + (b * LPD + PADL + m) * 2) = pk;
;             else *(u32x2*)(V + xrow_off + m) = pk;
.LBB0_1564:
	s_andn2_saveexec_b64 s[48:49], s[48:49]
	s_cbranch_execz .LBB0_1569
	ds_read_b128 v[82:85], v234
	s_waitcnt vmcnt(1)
	v_lshlrev_b32_e32 v98, 16, v136
	v_and_b32_e32 v136, 0xffff0000, v136
	s_waitcnt vmcnt(0)
	v_lshlrev_b32_e32 v135, 16, v204
	v_lshlrev_b32_e32 v147, 16, v134
	v_and_b32_e32 v146, 0xffff0000, v137
	s_waitcnt lgkmcnt(0)
	v_pk_add_f32 v[148:149], v[84:85], 0 op_sel_hi:[1,0]
	v_pk_add_f32 v[150:151], v[82:83], 0 op_sel_hi:[1,0]
	ds_read_b128 v[82:85], v234 offset:1024
	v_lshlrev_b32_e32 v137, 16, v137
	v_mov_b32_e32 v90, v93
	v_mov_b32_e32 v134, v136
	v_mov_b32_e32 v92, v93
	s_waitcnt lgkmcnt(0)
	v_pk_add_f32 v[148:149], v[148:149], v[84:85]
	v_pk_add_f32 v[150:151], v[150:151], v[82:83]
	ds_read_b128 v[82:85], v234 offset:2048
	v_pk_mul_f32 v[134:135], v[90:91], v[134:135]
	v_mov_b32_e32 v100, v101
	v_pk_fma_f32 v[134:135], v[90:91], v[98:99], v[134:135] op_sel:[0,0,1] op_sel_hi:[1,0,0]
	v_mov_b32_e32 v98, v99
	s_waitcnt lgkmcnt(0)
	v_pk_add_f32 v[148:149], v[148:149], v[84:85]
	v_pk_add_f32 v[150:151], v[150:151], v[82:83]
	ds_read_b128 v[82:85], v234 offset:3072
	v_mov_b32_e32 v90, v91
	v_pk_fma_f32 v[134:135], v[98:99], v[136:137], v[134:135] op_sel_hi:[0,1,1]
	v_pk_add_f32 v[134:135], v[100:101], v[134:135] op_sel_hi:[0,1]
	s_mov_b64 s[74:75], -1
	s_waitcnt lgkmcnt(0)
	v_pk_add_f32 v[148:149], v[148:149], v[84:85]
	v_pk_add_f32 v[150:151], v[150:151], v[82:83]
	ds_read_b128 v[82:85], v234 offset:4096
	s_and_b64 vcc, exec, s[72:73]
	s_waitcnt lgkmcnt(0)
	v_pk_add_f32 v[148:149], v[148:149], v[84:85]
	v_pk_add_f32 v[150:151], v[150:151], v[82:83]
	ds_read_b128 v[82:85], v234 offset:5120
	s_waitcnt lgkmcnt(0)
	v_pk_add_f32 v[148:149], v[148:149], v[84:85]
	v_pk_add_f32 v[150:151], v[150:151], v[82:83]
	ds_read_b128 v[82:85], v234 offset:6144
	s_waitcnt lgkmcnt(0)
	v_pk_add_f32 v[148:149], v[148:149], v[84:85]
	v_pk_add_f32 v[150:151], v[150:151], v[82:83]
	ds_read_b128 v[82:85], v234 offset:7168
	s_waitcnt lgkmcnt(0)
	v_pk_add_f32 v[84:85], v[148:149], v[84:85]
	v_pk_mov_b32 v[148:149], v[136:137], v[146:147] op_sel:[1,0]
	v_pk_add_f32 v[82:83], v[150:151], v[82:83]
	v_pk_mul_f32 v[148:149], v[92:93], v[148:149] op_sel_hi:[0,1]
	v_pk_fma_f32 v[136:137], v[90:91], v[136:137], v[148:149] op_sel_hi:[0,1,1]
	v_pk_fma_f32 v[136:137], v[98:99], v[146:147], v[136:137] op_sel_hi:[0,1,1]
	v_pk_add_f32 v[136:137], v[100:101], v[136:137] op_sel_hi:[0,1]
	v_pk_mul_f32 v[84:85], v[136:137], v[84:85]
	v_pk_mul_f32 v[82:83], v[134:135], v[82:83]
	s_nop 0
	v_cvt_pk_bf16_f32 v82, v82, v83
	v_cvt_pk_bf16_f32 v83, v84, v85
	s_cbranch_vccz .LBB0_1567
	global_store_dwordx2 v[162:163], v[82:83], off
	s_mov_b64 s[74:75], 0
